# placement: pool_in K-loop head moved by 64 bytes (on phase 0 + gate load hoist)
# speedup vs baseline: 1.0025x; 1.0025x over previous
; template <class Epi, class Sched, bool ALIGN_EPI = false, bool SP2 = false>
; __device__ __forceinline__ void gemm_phase(PG8_LAS unsigned char* lds, const Gemm g, const Sched& S, const Epi& E) {
;     ...
;         const bool has_next = S.next(ui + 1, nxt);
;         const char* nA = has_next ? PG8_ABASE(nxt) : cA; const char* nB = has_next ? (const char*)g.Bt + (size_t)nxt.pn * tstepB : cB;
;     ...
; #pragma unroll
;         for (int a = 0; a < 2; ++a)
; #pragma unroll
;             for (int b = 0; b < 2; ++b)
; #pragma unroll
;                 for (int m = 0; m < 4; ++m)
; #pragma unroll
;                     for (int n = 0; n < 2; ++n) acc[a][b][m][n] = (f32x4){0.f, 0.f, 0.f, 0.f};
;         cur = nxt; cA = nA; cB = nB; ++ui;
.LBB0_740:
	s_ashr_i32 s27, s26, 31
	s_lshl_b64 s[28:29], s[26:27], 21
	s_add_u32 s28, s44, s28
	s_addc_u32 s29, s45, s29
	s_and_b64 s[30:31], s[2:3], exec
	s_cselect_b32 s27, s29, s39
	s_cselect_b32 s63, s28, s38
	s_ashr_i32 s25, s24, 31
	s_lshl_b64 s[30:31], s[24:25], 21
	s_add_u32 s30, s46, s30
	s_addc_u32 s31, s47, s31
	s_and_b64 s[42:43], s[2:3], exec
	s_cselect_b32 s25, s31, s41
	s_cselect_b32 s64, s30, s40
	s_add_u32 s38, s38, 0x100080
	s_addc_u32 s39, s39, 0
	s_add_u32 s65, s40, 0x100
	v_mov_b32_e32 v2, 0
	s_addc_u32 s66, s41, 0
	s_mov_b32 s67, -2
	v_mov_b32_e32 v3, v2
	v_mov_b32_e32 v4, v2
	v_mov_b32_e32 v5, v2
	v_mov_b32_e32 v6, v2
	v_mov_b32_e32 v7, v2
	v_mov_b32_e32 v8, v2
	v_mov_b32_e32 v9, v2
	v_mov_b32_e32 v14, v2
	v_mov_b32_e32 v15, v2
	v_mov_b32_e32 v16, v2
	v_mov_b32_e32 v17, v2
	v_mov_b32_e32 v22, v2
	v_mov_b32_e32 v23, v2
	v_mov_b32_e32 v24, v2
	v_mov_b32_e32 v25, v2
	v_mov_b32_e32 v30, v2
	v_mov_b32_e32 v31, v2
	v_mov_b32_e32 v32, v2
	v_mov_b32_e32 v33, v2
	v_mov_b32_e32 v38, v2
	v_mov_b32_e32 v39, v2
	v_mov_b32_e32 v40, v2
	v_mov_b32_e32 v41, v2
	v_mov_b32_e32 v46, v2
	v_mov_b32_e32 v47, v2
	v_mov_b32_e32 v48, v2
	v_mov_b32_e32 v49, v2
	v_mov_b32_e32 v54, v2
	v_mov_b32_e32 v55, v2
	v_mov_b32_e32 v56, v2
	v_mov_b32_e32 v57, v2
	v_mov_b32_e32 v10, v2
	v_mov_b32_e32 v11, v2
	v_mov_b32_e32 v12, v2
	v_mov_b32_e32 v13, v2
	v_mov_b32_e32 v18, v2
	v_mov_b32_e32 v19, v2
	v_mov_b32_e32 v20, v2
	v_mov_b32_e32 v21, v2
	v_mov_b32_e32 v26, v2
	v_mov_b32_e32 v27, v2
	v_mov_b32_e32 v28, v2
	v_mov_b32_e32 v29, v2
	v_mov_b32_e32 v34, v2
	v_mov_b32_e32 v35, v2
	v_mov_b32_e32 v36, v2
	v_mov_b32_e32 v37, v2
	v_mov_b32_e32 v42, v2
	v_mov_b32_e32 v43, v2
	v_mov_b32_e32 v44, v2
	v_mov_b32_e32 v45, v2
	v_mov_b32_e32 v50, v2
	v_mov_b32_e32 v51, v2
	v_mov_b32_e32 v52, v2
	v_mov_b32_e32 v53, v2
	v_mov_b32_e32 v58, v2
	v_mov_b32_e32 v59, v2
	v_mov_b32_e32 v60, v2
	v_mov_b32_e32 v61, v2
	v_mov_b32_e32 v62, v2
	v_mov_b32_e32 v63, v2
	v_mov_b32_e32 v64, v2
	v_mov_b32_e32 v65, v2
	v_mov_b32_e32 v66, v2
	v_mov_b32_e32 v67, v2
	v_mov_b32_e32 v68, v2
	v_mov_b32_e32 v69, v2
	v_mov_b32_e32 v70, v2
	v_mov_b32_e32 v71, v2
	v_mov_b32_e32 v72, v2
	v_mov_b32_e32 v73, v2
	v_mov_b32_e32 v82, v2
	v_mov_b32_e32 v83, v2
	v_mov_b32_e32 v84, v2
	v_mov_b32_e32 v85, v2
	v_mov_b32_e32 v86, v2
	v_mov_b32_e32 v87, v2
	v_mov_b32_e32 v88, v2
	v_mov_b32_e32 v89, v2
	v_mov_b32_e32 v98, v2
	v_mov_b32_e32 v99, v2
	v_mov_b32_e32 v100, v2
	v_mov_b32_e32 v101, v2
	v_mov_b32_e32 v102, v2
	v_mov_b32_e32 v103, v2
	v_mov_b32_e32 v104, v2
	v_mov_b32_e32 v105, v2
	v_mov_b32_e32 v114, v2
	v_mov_b32_e32 v115, v2
	v_mov_b32_e32 v116, v2
	v_mov_b32_e32 v117, v2
	v_mov_b32_e32 v118, v2
	v_mov_b32_e32 v119, v2
	v_mov_b32_e32 v120, v2
	v_mov_b32_e32 v121, v2
	v_mov_b32_e32 v74, v2
	v_mov_b32_e32 v75, v2
	v_mov_b32_e32 v76, v2
	v_mov_b32_e32 v77, v2
	v_mov_b32_e32 v78, v2
	v_mov_b32_e32 v79, v2
	v_mov_b32_e32 v80, v2
	v_mov_b32_e32 v81, v2
	v_mov_b32_e32 v90, v2
	v_mov_b32_e32 v91, v2
	v_mov_b32_e32 v92, v2
	v_mov_b32_e32 v93, v2
	v_mov_b32_e32 v94, v2
	v_mov_b32_e32 v95, v2
	v_mov_b32_e32 v96, v2
	v_mov_b32_e32 v97, v2
	v_mov_b32_e32 v106, v2
	v_mov_b32_e32 v107, v2
	v_mov_b32_e32 v108, v2
	v_mov_b32_e32 v109, v2
	v_mov_b32_e32 v110, v2
	v_mov_b32_e32 v111, v2
	v_mov_b32_e32 v112, v2
	v_mov_b32_e32 v113, v2
	v_mov_b32_e32 v122, v2
	v_mov_b32_e32 v123, v2
	v_mov_b32_e32 v124, v2
	v_mov_b32_e32 v125, v2
	v_mov_b32_e32 v126, v2
	v_mov_b32_e32 v127, v2
	v_mov_b32_e32 v128, v2
	v_mov_b32_e32 v129, v2
	s_nop 0
	s_nop 0
	s_nop 0
	s_nop 0
	s_nop 0
	s_nop 0
	s_nop 0
	s_nop 0
	s_nop 0
	s_nop 0
	s_nop 0
	s_nop 0
	s_nop 0
	s_nop 0
	s_nop 0
	s_nop 0

; #define PG8_WAIT_V(n) asm volatile("s_waitcnt vmcnt(" #n ")" ::: "memory")
; #define PG8_BAR __builtin_amdgcn_s_barrier()
; template <class Epi, class Sched, bool ALIGN_EPI = false, bool SP2 = false>
; __device__ __forceinline__ void gemm_phase(PG8_LAS unsigned char* lds, const Gemm g, const Sched& S, const Epi& E) {
;     ...
;     PG8_WAIT_V(0);
;     if constexpr (!ALIGN_EPI) { if (wr == 0) PG8_BAR; }
;     PG8_BAR;
.LBB0_751:
	s_waitcnt vmcnt(0)
	s_barrier
	s_nop 0
	s_nop 0
	s_nop 0
	s_nop 0
	s_nop 0
	s_nop 0
	s_nop 0
	s_nop 0
	s_nop 0
	s_nop 0
	s_nop 0
	s_nop 0
	s_nop 0
	s_nop 0
	s_nop 0
	s_nop 0
